# attention K-fragment ds_reads interleaved pairwise with the QK MFMAs again (no 12-read burst), sum-triggered rescale kept
# speedup vs baseline: 1.0063x; 1.0063x over previous
; DI void attn_item(const Params& p, int item, char* smem) {
;     ...
;     const u16* Kc = Ks + cur * 64 * KSL;
;     const u16* Vc = Vs + cur * 64 * VSL;
;     f32x16 p0, p1;
; #pragma unroll
;     for (int i = 0; i < 16; ++i) { p0[i] = 0.f; p1[i] = 0.f; }
; #pragma unroll
;     for (int d0 = 0; d0 < 6; ++d0) {
;       const bf16x8 a0 = *(const bf16x8*)(Kc + r32 * KSL + d0 * 16 + hi * 8);
;       const bf16x8 a1 = *(const bf16x8*)(Kc + (32 + r32) * KSL + d0 * 16 + hi * 8);
;       p0 = __builtin_amdgcn_mfma_f32_32x32x16_bf16(a0, qr[d0], p0, 0, 0, 0);
;       p1 = __builtin_amdgcn_mfma_f32_32x32x16_bf16(a1, qr[d0], p1, 0, 0, 0);
;     }
;     float mx = p0[0];
; #pragma unroll
;     for (int i = 1; i < 16; ++i) mx = fmaxf(mx, p0[i]);
; #pragma unroll
;     for (int i = 0; i < 16; ++i) mx = fmaxf(mx, p1[i]);
;     { auto rr = __builtin_amdgcn_permlane32_swap(__float_as_uint(mx), __float_as_uint(mx), false, false);
;       mx = fmaxf(__uint_as_float(rr[0]), __uint_as_float(rr[1])); }
;     if (!__all(mx - mrun <= 8.f)) {
;       const float mn = fmaxf(mrun, mx);
;       const float alpha = __builtin_amdgcn_exp2f(mrun - mn);
;       mrun = mn; lrun *= alpha;
; #pragma unroll
;       for (int i = 0; i < 16; ++i) { o0[i] *= alpha; o1[i] *= alpha; }
;     }
;     float ps = 0.f;
; #pragma unroll
;     for (int i = 0; i < 16; ++i) { p0[i] = __builtin_amdgcn_exp2f(p0[i] - mrun); ps += p0[i]; }
; #pragma unroll
;     for (int i = 0; i < 16; ++i) { p1[i] = __builtin_amdgcn_exp2f(p1[i] - mrun); ps += p1[i]; }
.LBB0_531:
	ds_read_b128 v[48:51], v154
	ds_read_b128 v[52:55], v154 offset:32
	s_waitcnt lgkmcnt(0)
	v_mfma_f32_32x32x16_bf16 v[64:79], v[48:51], v[80:83], v[196:211]
	v_mfma_f32_32x32x16_bf16 v[64:79], v[52:55], v[84:87], v[64:79]
	ds_read_b128 v[48:51], v154 offset:64
	ds_read_b128 v[52:55], v154 offset:96
	s_waitcnt lgkmcnt(0)
	v_mfma_f32_32x32x16_bf16 v[64:79], v[48:51], v[88:91], v[64:79]
	v_mfma_f32_32x32x16_bf16 v[64:79], v[52:55], v[92:95], v[64:79]
	ds_read_b128 v[48:51], v154 offset:128
	ds_read_b128 v[52:55], v154 offset:160
	s_waitcnt lgkmcnt(0)
	v_mfma_f32_32x32x16_bf16 v[64:79], v[48:51], v[96:99], v[64:79]
	ds_read_b128 v[48:51], v154 offset:6656
	ds_read_b128 v[158:161], v154 offset:6688
	v_mfma_f32_32x32x16_bf16 v[64:79], v[52:55], v[100:103], v[64:79]
	s_waitcnt lgkmcnt(0)
	v_mfma_f32_32x32x16_bf16 v[48:63], v[48:51], v[80:83], v[196:211]
	v_mfma_f32_32x32x16_bf16 v[48:63], v[158:161], v[84:87], v[48:63]
	ds_read_b128 v[158:161], v154 offset:6720
	ds_read_b128 v[164:167], v154 offset:6752
	s_nop 7
	v_exp_f32_e32 v168, v64
	v_exp_f32_e32 v169, v65
	v_exp_f32_e32 v170, v66
	v_exp_f32_e32 v171, v67
	v_exp_f32_e32 v172, v68
	v_exp_f32_e32 v173, v69
	v_exp_f32_e32 v174, v70
	v_exp_f32_e32 v175, v71
	s_waitcnt lgkmcnt(0)
	v_mfma_f32_32x32x16_bf16 v[48:63], v[158:161], v[88:91], v[48:63]
	v_mfma_f32_32x32x16_bf16 v[48:63], v[164:167], v[92:95], v[48:63]
	ds_read_b128 v[158:161], v154 offset:6784
	ds_read_b128 v[164:167], v154 offset:6816
	v_exp_f32_e32 v176, v72
	v_exp_f32_e32 v177, v73
	v_exp_f32_e32 v178, v74
	v_exp_f32_e32 v179, v75
	v_exp_f32_e32 v180, v76
	v_exp_f32_e32 v181, v77
	v_exp_f32_e32 v182, v78
	v_exp_f32_e32 v183, v79
	s_waitcnt lgkmcnt(0)
	v_mfma_f32_32x32x16_bf16 v[48:63], v[158:161], v[96:99], v[48:63]
	v_mfma_f32_32x32x16_bf16 v[48:63], v[164:167], v[100:103], v[48:63]
	v_add_f32_e32 v0, v168, v169
	v_add_f32_e32 v0, v170, v0
	v_add_f32_e32 v0, v171, v0
	v_add_f32_e32 v0, v172, v0
	v_add_f32_e32 v0, v173, v0
	v_add_f32_e32 v0, v174, v0
	v_add_f32_e32 v0, v175, v0
	v_add_f32_e32 v0, v176, v0
	v_add_f32_e32 v0, v177, v0
	v_add_f32_e32 v0, v178, v0
	v_add_f32_e32 v0, v179, v0
	v_add_f32_e32 v0, v180, v0
	v_add_f32_e32 v0, v181, v0
	v_add_f32_e32 v0, v182, v0
	v_add_f32_e32 v0, v183, v0
	v_exp_f32_e32 v184, v48
	v_exp_f32_e32 v185, v49
	v_exp_f32_e32 v186, v50
	v_exp_f32_e32 v187, v51
	v_exp_f32_e32 v188, v52
	v_exp_f32_e32 v189, v53
	v_exp_f32_e32 v190, v54
	v_exp_f32_e32 v191, v55
	v_exp_f32_e32 v158, v56
	v_exp_f32_e32 v159, v57
	v_exp_f32_e32 v160, v58
	v_exp_f32_e32 v161, v59
	v_exp_f32_e32 v164, v60
	v_exp_f32_e32 v165, v61
	v_exp_f32_e32 v166, v62
	v_exp_f32_e32 v167, v63
	v_add_f32_e32 v0, v184, v0
	v_add_f32_e32 v0, v185, v0
	v_add_f32_e32 v0, v186, v0
	v_add_f32_e32 v0, v187, v0
	v_add_f32_e32 v0, v188, v0
	v_add_f32_e32 v0, v189, v0
	v_add_f32_e32 v0, v190, v0
	v_add_f32_e32 v0, v191, v0
	v_add_f32_e32 v0, v158, v0
	v_add_f32_e32 v0, v159, v0
	v_add_f32_e32 v0, v160, v0
	v_add_f32_e32 v0, v161, v0
	v_add_f32_e32 v0, v164, v0
	v_add_f32_e32 v0, v165, v0
	v_add_f32_e32 v0, v166, v0
	v_add_f32_e32 v0, v167, v0
	v_cmp_ge_f32_e32 vcc, s98, v0
	s_cmp_eq_u64 vcc, exec
	s_cbranch_scc1 .LBB0_533
; DI void attn_item(const Params& p, int item, char* smem) {
;     ...
;     float mx = p0[0];
; #pragma unroll
;     for (int i = 1; i < 16; ++i) mx = fmaxf(mx, p0[i]);
; #pragma unroll
;     for (int i = 0; i < 16; ++i) mx = fmaxf(mx, p1[i]);
;     { auto rr = __builtin_amdgcn_permlane32_swap(__float_as_uint(mx), __float_as_uint(mx), false, false);
;       mx = fmaxf(__uint_as_float(rr[0]), __uint_as_float(rr[1])); }
;     if (!__all(mx - mrun <= 8.f)) {
;       const float mn = fmaxf(mrun, mx);
;       const float alpha = __builtin_amdgcn_exp2f(mrun - mn);
;       mrun = mn; lrun *= alpha;
; #pragma unroll
;       for (int i = 0; i < 16; ++i) { o0[i] *= alpha; o1[i] *= alpha; }
;     }
;     float ps = 0.f;
; #pragma unroll
;     for (int i = 0; i < 16; ++i) { p0[i] = __builtin_amdgcn_exp2f(p0[i] - mrun); ps += p0[i]; }
; #pragma unroll
;     for (int i = 0; i < 16; ++i) { p1[i] = __builtin_amdgcn_exp2f(p1[i] - mrun); ps += p1[i]; }
	v_max_f32_e32 v10, v64, v65
	v_max3_f32 v10, v10, v66, v67
	v_max3_f32 v10, v10, v68, v69
	v_max3_f32 v10, v10, v70, v71
	v_max3_f32 v10, v10, v72, v73
	v_max3_f32 v10, v10, v74, v75
	v_max3_f32 v10, v10, v76, v77
	v_max3_f32 v10, v10, v78, v79
	v_max3_f32 v10, v10, v48, v49
	v_max3_f32 v10, v10, v50, v51
	v_max3_f32 v10, v10, v52, v53
	v_max3_f32 v10, v10, v54, v55
	v_max3_f32 v10, v10, v56, v57
	v_max3_f32 v10, v10, v58, v59
	v_max3_f32 v10, v10, v60, v61
	v_max3_f32 v10, v10, v62, v63
	v_mov_b32_e32 v11, v10
	s_nop 1
	v_permlane32_swap_b32_e32 v10, v11
	v_max_f32_e32 v10, v10, v11
	v_max_f32_e32 v11, s99, v10
	v_max_f32_e32 v10, 0, v11
	s_mov_b32 s98, 0x46000000
	v_exp_f32_e64 v10, -v10
	s_mov_b32 s99, 0
	v_sub_f32_e32 v196, v196, v11
	v_mul_f32_e32 v157, v157, v10
	v_pk_mul_f32 v[46:47], v[46:47], v[10:11] op_sel_hi:[1,0]
	v_pk_mul_f32 v[44:45], v[44:45], v[10:11] op_sel_hi:[1,0]
	v_pk_mul_f32 v[42:43], v[42:43], v[10:11] op_sel_hi:[1,0]
	v_pk_mul_f32 v[40:41], v[40:41], v[10:11] op_sel_hi:[1,0]
	v_pk_mul_f32 v[38:39], v[38:39], v[10:11] op_sel_hi:[1,0]
	v_pk_mul_f32 v[36:37], v[36:37], v[10:11] op_sel_hi:[1,0]
	v_pk_mul_f32 v[34:35], v[34:35], v[10:11] op_sel_hi:[1,0]
	v_pk_mul_f32 v[32:33], v[32:33], v[10:11] op_sel_hi:[1,0]
	v_pk_mul_f32 v[30:31], v[30:31], v[10:11] op_sel_hi:[1,0]
	v_pk_mul_f32 v[28:29], v[28:29], v[10:11] op_sel_hi:[1,0]
	v_pk_mul_f32 v[26:27], v[26:27], v[10:11] op_sel_hi:[1,0]
	v_pk_mul_f32 v[24:25], v[24:25], v[10:11] op_sel_hi:[1,0]
	v_pk_mul_f32 v[22:23], v[22:23], v[10:11] op_sel_hi:[1,0]
	v_pk_mul_f32 v[20:21], v[20:21], v[10:11] op_sel_hi:[1,0]
	v_pk_mul_f32 v[18:19], v[18:19], v[10:11] op_sel_hi:[1,0]
	v_pk_mul_f32 v[16:17], v[16:17], v[10:11] op_sel_hi:[1,0]
	v_mov_b32_e32 v197, v196
	v_mov_b32_e32 v198, v196
	v_mov_b32_e32 v199, v196
	v_mov_b32_e32 v200, v196
	v_mov_b32_e32 v201, v196
	v_mov_b32_e32 v202, v196
	v_mov_b32_e32 v203, v196
	v_mov_b32_e32 v204, v196
	v_mov_b32_e32 v205, v196
	v_mov_b32_e32 v206, v196
	v_mov_b32_e32 v207, v196
	v_mov_b32_e32 v208, v196
	v_mov_b32_e32 v209, v196
	v_mov_b32_e32 v210, v196
	v_mov_b32_e32 v211, v196
	v_sub_f32_e32 v64, v64, v11
	v_sub_f32_e32 v65, v65, v11
	v_sub_f32_e32 v66, v66, v11
	v_sub_f32_e32 v67, v67, v11
	v_sub_f32_e32 v68, v68, v11
	v_sub_f32_e32 v69, v69, v11
	v_sub_f32_e32 v70, v70, v11
	v_sub_f32_e32 v71, v71, v11
	v_sub_f32_e32 v72, v72, v11
	v_sub_f32_e32 v73, v73, v11
	v_sub_f32_e32 v74, v74, v11
	v_sub_f32_e32 v75, v75, v11
	v_sub_f32_e32 v76, v76, v11
	v_sub_f32_e32 v77, v77, v11
	v_sub_f32_e32 v78, v78, v11
	v_sub_f32_e32 v79, v79, v11
	v_sub_f32_e32 v48, v48, v11
	v_sub_f32_e32 v49, v49, v11
	v_sub_f32_e32 v50, v50, v11
	v_sub_f32_e32 v51, v51, v11
	v_sub_f32_e32 v52, v52, v11
	v_sub_f32_e32 v53, v53, v11
	v_sub_f32_e32 v54, v54, v11
	v_sub_f32_e32 v55, v55, v11
	v_sub_f32_e32 v56, v56, v11
	v_sub_f32_e32 v57, v57, v11
	v_sub_f32_e32 v58, v58, v11
	v_sub_f32_e32 v59, v59, v11
	v_sub_f32_e32 v60, v60, v11
	v_sub_f32_e32 v61, v61, v11
	v_sub_f32_e32 v62, v62, v11
	v_sub_f32_e32 v63, v63, v11
	v_exp_f32_e32 v168, v64
	v_exp_f32_e32 v169, v65
	v_exp_f32_e32 v170, v66
	v_exp_f32_e32 v171, v67
	v_exp_f32_e32 v172, v68
	v_exp_f32_e32 v173, v69
	v_exp_f32_e32 v174, v70
	v_exp_f32_e32 v175, v71
	v_exp_f32_e32 v176, v72
	v_exp_f32_e32 v177, v73
	v_exp_f32_e32 v178, v74
	v_exp_f32_e32 v179, v75
	v_exp_f32_e32 v180, v76
	v_exp_f32_e32 v181, v77
	v_exp_f32_e32 v182, v78
	v_exp_f32_e32 v183, v79
	v_exp_f32_e32 v184, v48
	v_exp_f32_e32 v185, v49
	v_exp_f32_e32 v186, v50
	v_exp_f32_e32 v187, v51
	v_exp_f32_e32 v188, v52
	v_exp_f32_e32 v189, v53
	v_exp_f32_e32 v190, v54
	v_exp_f32_e32 v191, v55
	v_exp_f32_e32 v158, v56
	v_exp_f32_e32 v159, v57
	v_exp_f32_e32 v160, v58
	v_exp_f32_e32 v161, v59
	v_exp_f32_e32 v164, v60
	v_exp_f32_e32 v165, v61
	v_exp_f32_e32 v166, v62
	v_exp_f32_e32 v167, v63
	v_add_f32_e32 v0, v168, v169
	v_add_f32_e32 v0, v170, v0
	v_add_f32_e32 v0, v171, v0
	v_add_f32_e32 v0, v172, v0
	v_add_f32_e32 v0, v173, v0
	v_add_f32_e32 v0, v174, v0
	v_add_f32_e32 v0, v175, v0
	v_add_f32_e32 v0, v176, v0
	v_add_f32_e32 v0, v177, v0
	v_add_f32_e32 v0, v178, v0
	v_add_f32_e32 v0, v179, v0
	v_add_f32_e32 v0, v180, v0
	v_add_f32_e32 v0, v181, v0
	v_add_f32_e32 v0, v182, v0
	v_add_f32_e32 v0, v183, v0
	v_add_f32_e32 v0, v184, v0
	v_add_f32_e32 v0, v185, v0
	v_add_f32_e32 v0, v186, v0
	v_add_f32_e32 v0, v187, v0
	v_add_f32_e32 v0, v188, v0
	v_add_f32_e32 v0, v189, v0
	v_add_f32_e32 v0, v190, v0
	v_add_f32_e32 v0, v191, v0
	v_add_f32_e32 v0, v158, v0
	v_add_f32_e32 v0, v159, v0
	v_add_f32_e32 v0, v160, v0
	v_add_f32_e32 v0, v161, v0
	v_add_f32_e32 v0, v164, v0
	v_add_f32_e32 v0, v165, v0
	v_add_f32_e32 v0, v166, v0
	v_add_f32_e32 v0, v167, v0

; DI void attn_item(const Params& p, int item, char* smem) {
;     ...
;     const u16* Kc = Ks + cur * 64 * KSL;
;     const u16* Vc = Vs + cur * 64 * VSL;
;     f32x16 p0, p1;
; #pragma unroll
;     for (int i = 0; i < 16; ++i) { p0[i] = 0.f; p1[i] = 0.f; }
; #pragma unroll
;     for (int d0 = 0; d0 < 6; ++d0) {
;       const bf16x8 a0 = *(const bf16x8*)(Kc + r32 * KSL + d0 * 16 + hi * 8);
;       const bf16x8 a1 = *(const bf16x8*)(Kc + (32 + r32) * KSL + d0 * 16 + hi * 8);
;       p0 = __builtin_amdgcn_mfma_f32_32x32x16_bf16(a0, qr[d0], p0, 0, 0, 0);
;       p1 = __builtin_amdgcn_mfma_f32_32x32x16_bf16(a1, qr[d0], p1, 0, 0, 0);
;     }
;     float mx = p0[0];
; #pragma unroll
;     for (int i = 1; i < 16; ++i) mx = fmaxf(mx, p0[i]);
; #pragma unroll
;     for (int i = 0; i < 16; ++i) mx = fmaxf(mx, p1[i]);
;     { auto rr = __builtin_amdgcn_permlane32_swap(__float_as_uint(mx), __float_as_uint(mx), false, false);
;       mx = fmaxf(__uint_as_float(rr[0]), __uint_as_float(rr[1])); }
;     if (!__all(mx - mrun <= 8.f)) {
;       const float mn = fmaxf(mrun, mx);
;       const float alpha = __builtin_amdgcn_exp2f(mrun - mn);
;       mrun = mn; lrun *= alpha;
; #pragma unroll
;       for (int i = 0; i < 16; ++i) { o0[i] *= alpha; o1[i] *= alpha; }
;     }
;     float ps = 0.f;
; #pragma unroll
;     for (int i = 0; i < 16; ++i) { p0[i] = __builtin_amdgcn_exp2f(p0[i] - mrun); ps += p0[i]; }
; #pragma unroll
;     for (int i = 0; i < 16; ++i) { p1[i] = __builtin_amdgcn_exp2f(p1[i] - mrun); ps += p1[i]; }
.LBB0_535:
	ds_read_b128 v[10:13], v154 offset:13312
	ds_read_b128 v[48:51], v154 offset:13344
	s_waitcnt lgkmcnt(0)
	v_mfma_f32_32x32x16_bf16 v[64:79], v[10:13], v[80:83], v[196:211]
	v_mfma_f32_32x32x16_bf16 v[64:79], v[48:51], v[84:87], v[64:79]
	ds_read_b128 v[10:13], v154 offset:13376
	ds_read_b128 v[48:51], v154 offset:13408
	s_waitcnt lgkmcnt(0)
	v_mfma_f32_32x32x16_bf16 v[64:79], v[10:13], v[88:91], v[64:79]
	v_mfma_f32_32x32x16_bf16 v[64:79], v[48:51], v[92:95], v[64:79]
	ds_read_b128 v[10:13], v154 offset:13440
	ds_read_b128 v[48:51], v154 offset:13472
	s_waitcnt lgkmcnt(0)
	v_mfma_f32_32x32x16_bf16 v[64:79], v[10:13], v[96:99], v[64:79]
	ds_read_b128 v[10:13], v154 offset:19968
	ds_read_b128 v[192:195], v154 offset:20000
	v_mfma_f32_32x32x16_bf16 v[64:79], v[48:51], v[100:103], v[64:79]
	s_waitcnt lgkmcnt(0)
	v_mfma_f32_32x32x16_bf16 v[48:63], v[10:13], v[80:83], v[196:211]
	v_mfma_f32_32x32x16_bf16 v[48:63], v[192:195], v[84:87], v[48:63]
	ds_read_b128 v[10:13], v154 offset:20032
	ds_read_b128 v[158:161], v154 offset:20064
	s_nop 7
	v_exp_f32_e32 v168, v64
	v_exp_f32_e32 v169, v65
	v_exp_f32_e32 v170, v66
	v_exp_f32_e32 v171, v67
	v_exp_f32_e32 v172, v68
	v_exp_f32_e32 v173, v69
	v_exp_f32_e32 v174, v70
	v_exp_f32_e32 v175, v71
	s_waitcnt lgkmcnt(0)
	v_mfma_f32_32x32x16_bf16 v[48:63], v[10:13], v[88:91], v[48:63]
	v_mfma_f32_32x32x16_bf16 v[48:63], v[158:161], v[92:95], v[48:63]
	ds_read_b128 v[10:13], v154 offset:20096
	ds_read_b128 v[158:161], v154 offset:20128
	v_exp_f32_e32 v176, v72
	v_exp_f32_e32 v177, v73
	v_exp_f32_e32 v178, v74
	v_exp_f32_e32 v179, v75
	v_exp_f32_e32 v180, v76
	v_exp_f32_e32 v181, v77
	v_exp_f32_e32 v182, v78
	v_exp_f32_e32 v183, v79
	s_waitcnt lgkmcnt(0)
	v_mfma_f32_32x32x16_bf16 v[48:63], v[10:13], v[96:99], v[48:63]
	v_mfma_f32_32x32x16_bf16 v[48:63], v[158:161], v[100:103], v[48:63]
	v_add_f32_e32 v0, v168, v169
	v_add_f32_e32 v0, v170, v0
	v_add_f32_e32 v0, v171, v0
	v_add_f32_e32 v0, v172, v0
	v_add_f32_e32 v0, v173, v0
	v_add_f32_e32 v0, v174, v0
	v_add_f32_e32 v0, v175, v0
	v_add_f32_e32 v0, v176, v0
	v_add_f32_e32 v0, v177, v0
	v_add_f32_e32 v0, v178, v0
	v_add_f32_e32 v0, v179, v0
	v_add_f32_e32 v0, v180, v0
	v_add_f32_e32 v0, v181, v0
	v_add_f32_e32 v0, v182, v0
	v_add_f32_e32 v0, v183, v0
	v_exp_f32_e32 v184, v48
	v_exp_f32_e32 v185, v49
	v_exp_f32_e32 v186, v50
	v_exp_f32_e32 v187, v51
	v_exp_f32_e32 v188, v52
	v_exp_f32_e32 v189, v53
	v_exp_f32_e32 v190, v54
	v_exp_f32_e32 v191, v55
	v_exp_f32_e32 v158, v56
	v_exp_f32_e32 v159, v57
	v_exp_f32_e32 v160, v58
	v_exp_f32_e32 v161, v59
	v_exp_f32_e32 v164, v60
	v_exp_f32_e32 v165, v61
	v_exp_f32_e32 v166, v62
	v_exp_f32_e32 v167, v63
	v_add_f32_e32 v0, v184, v0
	v_add_f32_e32 v0, v185, v0
	v_add_f32_e32 v0, v186, v0
	v_add_f32_e32 v0, v187, v0
	v_add_f32_e32 v0, v188, v0
	v_add_f32_e32 v0, v189, v0
	v_add_f32_e32 v0, v190, v0
	v_add_f32_e32 v0, v191, v0
	v_add_f32_e32 v0, v158, v0
	v_add_f32_e32 v0, v159, v0
	v_add_f32_e32 v0, v160, v0
	v_add_f32_e32 v0, v161, v0
	v_add_f32_e32 v0, v164, v0
	v_add_f32_e32 v0, v165, v0
	v_add_f32_e32 v0, v166, v0
	v_add_f32_e32 v0, v167, v0
	v_cmp_ge_f32_e32 vcc, s98, v0
	s_cmp_eq_u64 vcc, exec
	s_cbranch_scc1 .LBB0_537
; DI void attn_item(const Params& p, int item, char* smem) {
;     ...
;     float mx = p0[0];
; #pragma unroll
;     for (int i = 1; i < 16; ++i) mx = fmaxf(mx, p0[i]);
; #pragma unroll
;     for (int i = 0; i < 16; ++i) mx = fmaxf(mx, p1[i]);
;     { auto rr = __builtin_amdgcn_permlane32_swap(__float_as_uint(mx), __float_as_uint(mx), false, false);
;       mx = fmaxf(__uint_as_float(rr[0]), __uint_as_float(rr[1])); }
;     if (!__all(mx - mrun <= 8.f)) {
;       const float mn = fmaxf(mrun, mx);
;       const float alpha = __builtin_amdgcn_exp2f(mrun - mn);
;       mrun = mn; lrun *= alpha;
; #pragma unroll
;       for (int i = 0; i < 16; ++i) { o0[i] *= alpha; o1[i] *= alpha; }
;     }
;     float ps = 0.f;
; #pragma unroll
;     for (int i = 0; i < 16; ++i) { p0[i] = __builtin_amdgcn_exp2f(p0[i] - mrun); ps += p0[i]; }
; #pragma unroll
;     for (int i = 0; i < 16; ++i) { p1[i] = __builtin_amdgcn_exp2f(p1[i] - mrun); ps += p1[i]; }
	v_max_f32_e32 v10, v64, v65
	v_max3_f32 v10, v10, v66, v67
	v_max3_f32 v10, v10, v68, v69
	v_max3_f32 v10, v10, v70, v71
	v_max3_f32 v10, v10, v72, v73
	v_max3_f32 v10, v10, v74, v75
	v_max3_f32 v10, v10, v76, v77
	v_max3_f32 v10, v10, v78, v79
	v_max3_f32 v10, v10, v48, v49
	v_max3_f32 v10, v10, v50, v51
	v_max3_f32 v10, v10, v52, v53
	v_max3_f32 v10, v10, v54, v55
	v_max3_f32 v10, v10, v56, v57
	v_max3_f32 v10, v10, v58, v59
	v_max3_f32 v10, v10, v60, v61
	v_max3_f32 v10, v10, v62, v63
	v_mov_b32_e32 v11, v10
	s_nop 1
	v_permlane32_swap_b32_e32 v10, v11
	v_max_f32_e32 v10, v10, v11
	v_max_f32_e32 v11, s99, v10
	v_max_f32_e32 v10, 0, v11
	s_mov_b32 s98, 0x46000000
	v_exp_f32_e64 v10, -v10
	s_mov_b32 s99, 0
	v_sub_f32_e32 v196, v196, v11
	v_mul_f32_e32 v157, v157, v10
	v_pk_mul_f32 v[46:47], v[46:47], v[10:11] op_sel_hi:[1,0]
	v_pk_mul_f32 v[44:45], v[44:45], v[10:11] op_sel_hi:[1,0]
	v_pk_mul_f32 v[42:43], v[42:43], v[10:11] op_sel_hi:[1,0]
	v_pk_mul_f32 v[40:41], v[40:41], v[10:11] op_sel_hi:[1,0]
	v_pk_mul_f32 v[38:39], v[38:39], v[10:11] op_sel_hi:[1,0]
	v_pk_mul_f32 v[36:37], v[36:37], v[10:11] op_sel_hi:[1,0]
	v_pk_mul_f32 v[34:35], v[34:35], v[10:11] op_sel_hi:[1,0]
	v_pk_mul_f32 v[32:33], v[32:33], v[10:11] op_sel_hi:[1,0]
	v_pk_mul_f32 v[30:31], v[30:31], v[10:11] op_sel_hi:[1,0]
	v_pk_mul_f32 v[28:29], v[28:29], v[10:11] op_sel_hi:[1,0]
	v_pk_mul_f32 v[26:27], v[26:27], v[10:11] op_sel_hi:[1,0]
	v_pk_mul_f32 v[24:25], v[24:25], v[10:11] op_sel_hi:[1,0]
	v_pk_mul_f32 v[22:23], v[22:23], v[10:11] op_sel_hi:[1,0]
	v_pk_mul_f32 v[20:21], v[20:21], v[10:11] op_sel_hi:[1,0]
	v_pk_mul_f32 v[18:19], v[18:19], v[10:11] op_sel_hi:[1,0]
	v_pk_mul_f32 v[16:17], v[16:17], v[10:11] op_sel_hi:[1,0]
	v_mov_b32_e32 v197, v196
	v_mov_b32_e32 v198, v196
	v_mov_b32_e32 v199, v196
	v_mov_b32_e32 v200, v196
	v_mov_b32_e32 v201, v196
	v_mov_b32_e32 v202, v196
	v_mov_b32_e32 v203, v196
	v_mov_b32_e32 v204, v196
	v_mov_b32_e32 v205, v196
	v_mov_b32_e32 v206, v196
	v_mov_b32_e32 v207, v196
	v_mov_b32_e32 v208, v196
	v_mov_b32_e32 v209, v196
	v_mov_b32_e32 v210, v196
	v_mov_b32_e32 v211, v196
	v_sub_f32_e32 v64, v64, v11
	v_sub_f32_e32 v65, v65, v11
	v_sub_f32_e32 v66, v66, v11
	v_sub_f32_e32 v67, v67, v11
	v_sub_f32_e32 v68, v68, v11
	v_sub_f32_e32 v69, v69, v11
	v_sub_f32_e32 v70, v70, v11
	v_sub_f32_e32 v71, v71, v11
	v_sub_f32_e32 v72, v72, v11
	v_sub_f32_e32 v73, v73, v11
	v_sub_f32_e32 v74, v74, v11
	v_sub_f32_e32 v75, v75, v11
	v_sub_f32_e32 v76, v76, v11
	v_sub_f32_e32 v77, v77, v11
	v_sub_f32_e32 v78, v78, v11
	v_sub_f32_e32 v79, v79, v11
	v_sub_f32_e32 v48, v48, v11
	v_sub_f32_e32 v49, v49, v11
	v_sub_f32_e32 v50, v50, v11
	v_sub_f32_e32 v51, v51, v11
	v_sub_f32_e32 v52, v52, v11
	v_sub_f32_e32 v53, v53, v11
	v_sub_f32_e32 v54, v54, v11
	v_sub_f32_e32 v55, v55, v11
	v_sub_f32_e32 v56, v56, v11
	v_sub_f32_e32 v57, v57, v11
	v_sub_f32_e32 v58, v58, v11
	v_sub_f32_e32 v59, v59, v11
	v_sub_f32_e32 v60, v60, v11
	v_sub_f32_e32 v61, v61, v11
	v_sub_f32_e32 v62, v62, v11
	v_sub_f32_e32 v63, v63, v11
	v_exp_f32_e32 v168, v64
	v_exp_f32_e32 v169, v65
	v_exp_f32_e32 v170, v66
	v_exp_f32_e32 v171, v67
	v_exp_f32_e32 v172, v68
	v_exp_f32_e32 v173, v69
	v_exp_f32_e32 v174, v70
	v_exp_f32_e32 v175, v71
	v_exp_f32_e32 v176, v72
	v_exp_f32_e32 v177, v73
	v_exp_f32_e32 v178, v74
	v_exp_f32_e32 v179, v75
	v_exp_f32_e32 v180, v76
	v_exp_f32_e32 v181, v77
	v_exp_f32_e32 v182, v78
	v_exp_f32_e32 v183, v79
	v_exp_f32_e32 v184, v48
	v_exp_f32_e32 v185, v49
	v_exp_f32_e32 v186, v50
	v_exp_f32_e32 v187, v51
	v_exp_f32_e32 v188, v52
	v_exp_f32_e32 v189, v53
	v_exp_f32_e32 v190, v54
	v_exp_f32_e32 v191, v55
	v_exp_f32_e32 v158, v56
	v_exp_f32_e32 v159, v57
	v_exp_f32_e32 v160, v58
	v_exp_f32_e32 v161, v59
	v_exp_f32_e32 v164, v60
	v_exp_f32_e32 v165, v61
	v_exp_f32_e32 v166, v62
	v_exp_f32_e32 v167, v63
	v_add_f32_e32 v0, v168, v169
	v_add_f32_e32 v0, v170, v0
	v_add_f32_e32 v0, v171, v0
	v_add_f32_e32 v0, v172, v0
	v_add_f32_e32 v0, v173, v0
	v_add_f32_e32 v0, v174, v0
	v_add_f32_e32 v0, v175, v0
	v_add_f32_e32 v0, v176, v0
	v_add_f32_e32 v0, v177, v0
	v_add_f32_e32 v0, v178, v0
	v_add_f32_e32 v0, v179, v0
	v_add_f32_e32 v0, v180, v0
	v_add_f32_e32 v0, v181, v0
	v_add_f32_e32 v0, v182, v0
	v_add_f32_e32 v0, v183, v0
	v_add_f32_e32 v0, v184, v0
	v_add_f32_e32 v0, v185, v0
	v_add_f32_e32 v0, v186, v0
	v_add_f32_e32 v0, v187, v0
	v_add_f32_e32 v0, v188, v0
	v_add_f32_e32 v0, v189, v0
	v_add_f32_e32 v0, v190, v0
	v_add_f32_e32 v0, v191, v0
	v_add_f32_e32 v0, v158, v0
	v_add_f32_e32 v0, v159, v0
	v_add_f32_e32 v0, v160, v0
	v_add_f32_e32 v0, v161, v0
	v_add_f32_e32 v0, v164, v0
	v_add_f32_e32 v0, v165, v0
	v_add_f32_e32 v0, v166, v0
	v_add_f32_e32 v0, v167, v0
